# speedup vs baseline: 1.0202x; 1.0120x over previous
; __device__ __forceinline__ float sigmoidf_(float x) { return __builtin_amdgcn_rcpf(1.0f + __expf(-x)); }
; __device__ __forceinline__ void gemm_run(const GemmDesc& g, char* shm) {
;     ...
;         if (base) {
; #pragma unroll
;           for (int m = 0; m < 8; ++m)
; #pragma unroll
;             for (int n = 0; n < 4; ++n) {
;               const int row = brow + wr * 128 + m * 16 + fr;
;               float t0 = acc[m][n][0], t1 = acc[m][n][1], t2 = acc[m][n][2], t3 = acc[m][n][3];
;               if (act == 1) { t0 = tanhf(t0); t1 = tanhf(t1); t2 = tanhf(t2); t3 = tanhf(t3); }
;               else if (act == 2) { t0 = sigmoidf_(t0); t1 = sigmoidf_(t1); t2 = sigmoidf_(t2); t3 = sigmoidf_(t3); }
;               uint2 o; o.x = pack2(t0, t1); o.y = pack2(t2, t3);
;               *(uint2*)(base + (size_t)row * ld + off + n * 16 + fq * 4) = o;
;             }
.LBB0_322:
	s_add_i32 s6, s68, 0xfffffc00
	s_mov_b64 s[80:81], 0x400
	s_mov_b64 s[76:77], 0
	s_mov_b64 s[4:5], 0
	s_mov_b64 s[62:63], s[74:75]
	s_cmp_eq_u64 s[62:63], 0
	s_cbranch_scc1 .LBB0_1028
	s_branch .LBB0_323
.Lr1_fast:
	v_and_b32_e32 v204, 63, v135
	v_and_b32_e32 v205, 15, v204
	v_lshrrev_b32_e32 v206, 4, v204
	v_lshrrev_b32_e32 v207, 3, v204
	v_and_b32_e32 v208, 7, v204
	v_lshrrev_b32_e32 v209, 8, v135
	v_bfe_u32 v210, v135, 6, 2
	v_lshrrev_b32_e32 v211, 6, v135
	v_lshlrev_b32_e32 v211, 11, v211
	v_add_u32_e32 v211, 0x20000, v211
	v_lshrrev_b32_e32 v212, 1, v206
	v_and_b32_e32 v213, 7, v205
	v_xor_b32_e32 v212, v212, v213
	v_lshlrev_b32_e32 v212, 4, v212
	v_and_b32_e32 v213, 1, v206
	v_lshl_add_u32 v212, v213, 3, v212
	v_lshl_add_u32 v212, v205, 7, v212
	v_add_u32_e32 v148, v211, v212
	v_xor_b32_e32 v149, 32, v148
	v_xor_b32_e32 v150, 64, v148
	v_xor_b32_e32 v151, 0x60, v148
	v_xor_b32_e32 v212, v208, v207
	v_lshlrev_b32_e32 v212, 4, v212
	v_lshl_add_u32 v212, v207, 7, v212
	v_add_u32_e32 v156, v211, v212
	v_lshl_add_u32 v212, v209, 7, v207
	v_add_u32_e32 v212, s39, v212
	v_lshlrev_b32_e32 v213, 3, v208
	v_add_u32_e32 v213, s6, v213
	v_mul_lo_u32 v212, v212, s80
	v_add_lshl_u32 v146, v212, v213, 1
	s_lshl_b32 s4, s80, 4
	s_lshl_b32 s5, s80, 5
	v_add_u32_e32 v147, s4, v146
	v_cvt_pk_bf16_f32 v204, v124, v125
	v_cvt_pk_bf16_f32 v205, v126, v127
	ds_write_b64 v148, v[204:205]
	v_cvt_pk_bf16_f32 v206, v120, v121
	v_cvt_pk_bf16_f32 v207, v122, v123
	ds_write_b64 v149, v[206:207]
	v_cvt_pk_bf16_f32 v208, v116, v117
	v_cvt_pk_bf16_f32 v209, v118, v119
	ds_write_b64 v150, v[208:209]
	v_cvt_pk_bf16_f32 v210, v112, v113
	v_cvt_pk_bf16_f32 v211, v114, v115
	ds_write_b64 v151, v[210:211]
	ds_read_b128 v[236:239], v156
	ds_read_b128 v[240:243], v156 offset:1024
	v_cvt_pk_bf16_f32 v204, v108, v109
	v_cvt_pk_bf16_f32 v205, v110, v111
	ds_write_b64 v148, v[204:205]
	v_cvt_pk_bf16_f32 v206, v104, v105
	v_cvt_pk_bf16_f32 v207, v106, v107
	ds_write_b64 v149, v[206:207]
	v_cvt_pk_bf16_f32 v208, v100, v101
	v_cvt_pk_bf16_f32 v209, v102, v103
	ds_write_b64 v150, v[208:209]
	v_cvt_pk_bf16_f32 v210, v96, v97
	v_cvt_pk_bf16_f32 v211, v98, v99
	ds_write_b64 v151, v[210:211]
	s_waitcnt lgkmcnt(4)
	global_store_dwordx4 v146, v[236:239], s[62:63]
	global_store_dwordx4 v147, v[240:243], s[62:63]
	v_add_u32_e32 v146, s5, v146
	v_add_u32_e32 v147, s5, v147
	ds_read_b128 v[128:131], v156
	ds_read_b128 v[152:155], v156 offset:1024
	v_cvt_pk_bf16_f32 v204, v92, v93
	v_cvt_pk_bf16_f32 v205, v94, v95
	ds_write_b64 v148, v[204:205]
	v_cvt_pk_bf16_f32 v206, v88, v89
	v_cvt_pk_bf16_f32 v207, v90, v91
	ds_write_b64 v149, v[206:207]
	v_cvt_pk_bf16_f32 v208, v84, v85
	v_cvt_pk_bf16_f32 v209, v86, v87
	ds_write_b64 v150, v[208:209]
	v_cvt_pk_bf16_f32 v210, v80, v81
	v_cvt_pk_bf16_f32 v211, v82, v83
	ds_write_b64 v151, v[210:211]
	s_waitcnt lgkmcnt(4)
	global_store_dwordx4 v146, v[128:131], s[62:63]
	global_store_dwordx4 v147, v[152:155], s[62:63]
	v_add_u32_e32 v146, s5, v146
	v_add_u32_e32 v147, s5, v147
	ds_read_b128 v[236:239], v156
	ds_read_b128 v[240:243], v156 offset:1024
	v_cvt_pk_bf16_f32 v204, v76, v77
	v_cvt_pk_bf16_f32 v205, v78, v79
	ds_write_b64 v148, v[204:205]
	v_cvt_pk_bf16_f32 v206, v72, v73
	v_cvt_pk_bf16_f32 v207, v74, v75
	ds_write_b64 v149, v[206:207]
	v_cvt_pk_bf16_f32 v208, v68, v69
	v_cvt_pk_bf16_f32 v209, v70, v71
	ds_write_b64 v150, v[208:209]
	v_cvt_pk_bf16_f32 v210, v64, v65
	v_cvt_pk_bf16_f32 v211, v66, v67
	ds_write_b64 v151, v[210:211]
	s_waitcnt lgkmcnt(4)
	global_store_dwordx4 v146, v[236:239], s[62:63]
	global_store_dwordx4 v147, v[240:243], s[62:63]
	v_add_u32_e32 v146, s5, v146
	v_add_u32_e32 v147, s5, v147
	ds_read_b128 v[128:131], v156
	ds_read_b128 v[152:155], v156 offset:1024
	v_cvt_pk_bf16_f32 v204, v60, v61
	v_cvt_pk_bf16_f32 v205, v62, v63
	ds_write_b64 v148, v[204:205]
	v_cvt_pk_bf16_f32 v206, v56, v57
	v_cvt_pk_bf16_f32 v207, v58, v59
	ds_write_b64 v149, v[206:207]
	v_cvt_pk_bf16_f32 v208, v52, v53
	v_cvt_pk_bf16_f32 v209, v54, v55
	ds_write_b64 v150, v[208:209]
	v_cvt_pk_bf16_f32 v210, v48, v49
	v_cvt_pk_bf16_f32 v211, v50, v51
	ds_write_b64 v151, v[210:211]
	s_waitcnt lgkmcnt(4)
	global_store_dwordx4 v146, v[128:131], s[62:63]
	global_store_dwordx4 v147, v[152:155], s[62:63]
	v_add_u32_e32 v146, s5, v146
	v_add_u32_e32 v147, s5, v147
	ds_read_b128 v[236:239], v156
	ds_read_b128 v[240:243], v156 offset:1024
	v_cvt_pk_bf16_f32 v204, v44, v45
	v_cvt_pk_bf16_f32 v205, v46, v47
	ds_write_b64 v148, v[204:205]
	v_cvt_pk_bf16_f32 v206, v40, v41
	v_cvt_pk_bf16_f32 v207, v42, v43
	ds_write_b64 v149, v[206:207]
	v_cvt_pk_bf16_f32 v208, v36, v37
	v_cvt_pk_bf16_f32 v209, v38, v39
	ds_write_b64 v150, v[208:209]
	v_cvt_pk_bf16_f32 v210, v32, v33
	v_cvt_pk_bf16_f32 v211, v34, v35
	ds_write_b64 v151, v[210:211]
	s_waitcnt lgkmcnt(4)
	global_store_dwordx4 v146, v[236:239], s[62:63]
	global_store_dwordx4 v147, v[240:243], s[62:63]
	v_add_u32_e32 v146, s5, v146
	v_add_u32_e32 v147, s5, v147
	ds_read_b128 v[128:131], v156
	ds_read_b128 v[152:155], v156 offset:1024
	v_cvt_pk_bf16_f32 v204, v28, v29
	v_cvt_pk_bf16_f32 v205, v30, v31
	ds_write_b64 v148, v[204:205]
	v_cvt_pk_bf16_f32 v206, v24, v25
	v_cvt_pk_bf16_f32 v207, v26, v27
	ds_write_b64 v149, v[206:207]
	v_cvt_pk_bf16_f32 v208, v20, v21
	v_cvt_pk_bf16_f32 v209, v22, v23
	ds_write_b64 v150, v[208:209]
	v_cvt_pk_bf16_f32 v210, v16, v17
	v_cvt_pk_bf16_f32 v211, v18, v19
	ds_write_b64 v151, v[210:211]
	s_waitcnt lgkmcnt(4)
	global_store_dwordx4 v146, v[128:131], s[62:63]
	global_store_dwordx4 v147, v[152:155], s[62:63]
	v_add_u32_e32 v146, s5, v146
	v_add_u32_e32 v147, s5, v147
	ds_read_b128 v[236:239], v156
	ds_read_b128 v[240:243], v156 offset:1024
	v_cvt_pk_bf16_f32 v204, v12, v13
	v_cvt_pk_bf16_f32 v205, v14, v15
	ds_write_b64 v148, v[204:205]
	v_cvt_pk_bf16_f32 v206, v8, v9
	v_cvt_pk_bf16_f32 v207, v10, v11
	ds_write_b64 v149, v[206:207]
	v_cvt_pk_bf16_f32 v208, v4, v5
	v_cvt_pk_bf16_f32 v209, v6, v7
	ds_write_b64 v150, v[208:209]
	v_cvt_pk_bf16_f32 v210, v0, v1
	v_cvt_pk_bf16_f32 v211, v2, v3
	ds_write_b64 v151, v[210:211]
	s_waitcnt lgkmcnt(4)
	global_store_dwordx4 v146, v[236:239], s[62:63]
	global_store_dwordx4 v147, v[240:243], s[62:63]
	v_add_u32_e32 v146, s5, v146
	v_add_u32_e32 v147, s5, v147
	ds_read_b128 v[128:131], v156
	ds_read_b128 v[152:155], v156 offset:1024
	s_waitcnt lgkmcnt(0)
	global_store_dwordx4 v146, v[128:131], s[62:63]
	global_store_dwordx4 v147, v[152:155], s[62:63]
	s_branch .LBB0_261
; __device__ __forceinline__ float sigmoidf_(float x) { return __builtin_amdgcn_rcpf(1.0f + __expf(-x)); }
; __device__ __forceinline__ void gemm_run(const GemmDesc& g, char* shm) {
;     ...
;         if (base) {
; #pragma unroll
;           for (int m = 0; m < 8; ++m)
; #pragma unroll
;             for (int n = 0; n < 4; ++n) {
;               const int row = brow + wr * 128 + m * 16 + fr;
;               float t0 = acc[m][n][0], t1 = acc[m][n][1], t2 = acc[m][n][2], t3 = acc[m][n][3];
;               if (act == 1) { t0 = tanhf(t0); t1 = tanhf(t1); t2 = tanhf(t2); t3 = tanhf(t3); }
;               else if (act == 2) { t0 = sigmoidf_(t0); t1 = sigmoidf_(t1); t2 = sigmoidf_(t2); t3 = sigmoidf_(t3); }
.LBB0_323:
	s_or_b64 s[68:69], s[4:5], s[76:77]
	s_cmp_eq_u64 s[68:69], 0
	s_cbranch_scc1 .Lr1_fast
	s_xor_b64 s[60:61], s[4:5], -1
	v_cndmask_b32_e64 v128, 0, 1, s[76:77]
	s_mov_b64 s[68:69], -1
	s_and_b64 vcc, exec, s[60:61]
	v_cmp_ne_u32_e64 s[4:5], 1, v128
	s_cbranch_vccz .LBB0_327
	s_and_b64 vcc, exec, s[4:5]
	v_mov_b32_e32 v149, v127
	v_mov_b32_e32 v147, v126
	v_mov_b32_e32 v148, v125
	v_mov_b32_e32 v146, v124
	s_cbranch_vccnz .LBB0_326
	v_mul_f32_e32 v128, 0xbfb8aa3b, v124
	v_exp_f32_e32 v128, v128
	v_mul_f32_e32 v129, 0xbfb8aa3b, v125
	v_mul_f32_e32 v130, 0xbfb8aa3b, v127
	v_exp_f32_e32 v129, v129
	v_add_f32_e32 v128, 1.0, v128
	v_rcp_f32_e32 v146, v128
	v_mul_f32_e32 v128, 0xbfb8aa3b, v126
	v_exp_f32_e32 v128, v128
	v_exp_f32_e32 v130, v130
	v_add_f32_e32 v129, 1.0, v129
	v_rcp_f32_e32 v148, v129
	v_add_f32_e32 v128, 1.0, v128
	v_rcp_f32_e32 v147, v128
	v_add_f32_e32 v128, 1.0, v130
	v_rcp_f32_e32 v149, v128
